# v044 + 112 B of s_nop after the SGU loop so everything behind it sits 256 B later than in v027 (code placement check of the deferred-store variant)
# speedup vs baseline: 1.0004x; 1.0004x over previous
.LBB0_770:
	s_nop 0
	s_nop 0
	s_nop 0
	s_nop 0
	s_nop 0
	s_nop 0
	s_nop 0
	s_nop 0
	s_nop 0
	s_nop 0
	s_nop 0
	s_nop 0
	s_nop 0
	s_nop 0
	s_nop 0
	s_nop 0
	s_nop 0
	s_nop 0
	s_nop 0
	s_nop 0
	s_nop 0
	s_nop 0
	s_nop 0
	s_nop 0
	s_nop 0
	s_nop 0
	s_nop 0
	s_nop 0
	global_store_dwordx2 v[246:247], v[230:231], off
	global_store_dwordx2 v[246:247], v[232:233], off offset:32
	global_store_dwordx2 v[246:247], v[234:235], off offset:64
	global_store_dwordx2 v[246:247], v[236:237], off offset:96
	global_store_dwordx2 v[246:247], v[238:239], off offset:128
	global_store_dwordx2 v[246:247], v[240:241], off offset:160
	global_store_dwordx2 v[246:247], v[242:243], off offset:192
	global_store_dwordx2 v[246:247], v[244:245], off offset:224
	s_waitcnt lgkmcnt(0)
	s_cmp_lg_u32 s10, 0
	s_mov_b64 s[6:7], -1
	s_barrier
	s_cbranch_scc0 .LBB0_856
	v_add_u32_e32 v4, s66, v225
	v_ashrrev_i32_e32 v2, 31, v4
	v_lshrrev_b32_e32 v2, 20, v2
	v_add_u32_e32 v2, v4, v2
	v_and_b32_e32 v2, 0xfffff000, v2
	v_sub_u32_e32 v146, v4, v2
	v_mov_b64_e32 v[2:3], s[58:59]
	v_mad_i64_i32 v[2:3], s[6:7], v4, s97, v[2:3]
	v_mov_b32_e32 v127, v163
	v_lshl_add_u64 v[2:3], v[2:3], 0, v[126:127]
	s_mov_b64 s[6:7], 0x1c00
	v_lshl_add_u64 v[68:69], v[2:3], 0, s[6:7]
	v_mov_b32_e32 v12, 0
	v_cmp_lt_i32_e64 s[12:13], 0, v146
	v_mov_b32_e32 v16, 0
	v_mov_b32_e32 v17, 0
	v_mov_b32_e32 v18, 0
	v_mov_b32_e32 v19, 0
	s_and_saveexec_b64 s[6:7], s[12:13]
	s_cbranch_execz .LBB0_773
	v_add_co_u32_e32 v2, vcc, 0xffffd000, v68
	s_nop 1
	v_addc_co_u32_e32 v3, vcc, -1, v69, vcc
	global_load_dwordx4 v[16:19], v[2:3], off offset:-2048
